# GEMM K-loop: extra early stage-free barrier so the next LDS-DMA burst is issued while the previous one lands
# baseline (speedup 1.0000x reference)
.Lg42_loop:
	s_and_b32 s17, s16, 0x8000
	s_xor_b32 s18, s17, 0x8000
	v_add_u32_e32 v132, v134, v84
	v_add_u32_e32 v133, v135, v84
	ds_read_b128 v[152:155], v132
	ds_read_b128 v[156:159], v132 offset:2048
	ds_read_b128 v[160:163], v132 offset:4096
	ds_read_b128 v[164:167], v132 offset:6144
	s_waitcnt lgkmcnt(4)
	v_mfma_f32_16x16x32_bf16 v[60:63], v[88:91], v[92:95], v[60:63]
	v_mfma_f32_16x16x32_bf16 v[56:59], v[88:91], v[100:103], v[56:59]
	v_mfma_f32_16x16x32_bf16 v[52:55], v[88:91], v[108:111], v[52:55]
	v_mfma_f32_16x16x32_bf16 v[48:51], v[88:91], v[116:119], v[48:51]
	ds_read_b128 v[168:171], v133 offset:16384
	ds_read_b128 v[172:175], v133 offset:18432
	ds_read_b128 v[176:179], v133 offset:20480
	ds_read_b128 v[180:183], v133 offset:22528
	v_add_u32_e32 v128, s17, v82
	s_add_i32 s17, s18, 32
	v_add_u32_e32 v134, s17, v85
	v_add_u32_e32 v135, s17, v83
	v_readfirstlane_b32 s18, v128
	s_waitcnt lgkmcnt(0)
	s_barrier
	v_lshl_add_u64 v[130:131], v[64:65], 0, s[42:43]
	s_mov_b32 m0, s18
	s_nop 0
	global_load_lds_dwordx4 v[130:131], off
	v_mfma_f32_16x16x32_bf16 v[44:47], v[96:99], v[92:95], v[44:47]
	v_lshl_add_u64 v[130:131], v[72:73], 0, s[42:43]
	s_add_i32 m0, s18, 0x4000
	s_nop 0
	global_load_lds_dwordx4 v[130:131], off
	v_mfma_f32_16x16x32_bf16 v[40:43], v[96:99], v[100:103], v[40:43]
	v_mfma_f32_16x16x32_bf16 v[36:39], v[96:99], v[108:111], v[36:39]
	v_lshl_add_u64 v[130:131], v[66:67], 0, s[42:43]
	s_add_i32 m0, s18, 0x400
	s_nop 0
	global_load_lds_dwordx4 v[130:131], off
	v_mfma_f32_16x16x32_bf16 v[32:35], v[96:99], v[116:119], v[32:35]
	v_lshl_add_u64 v[130:131], v[74:75], 0, s[42:43]
	s_add_i32 m0, s18, 0x4400
	s_nop 0
	global_load_lds_dwordx4 v[130:131], off
	v_mfma_f32_16x16x32_bf16 v[28:31], v[104:107], v[92:95], v[28:31]
	v_mfma_f32_16x16x32_bf16 v[24:27], v[104:107], v[100:103], v[24:27]
	v_lshl_add_u64 v[130:131], v[68:69], 0, s[42:43]
	s_add_i32 m0, s18, 0x800
	s_nop 0
	global_load_lds_dwordx4 v[130:131], off
	v_mfma_f32_16x16x32_bf16 v[20:23], v[104:107], v[108:111], v[20:23]
	v_lshl_add_u64 v[130:131], v[76:77], 0, s[42:43]
	s_add_i32 m0, s18, 0x4800
	s_nop 0
	global_load_lds_dwordx4 v[130:131], off
	v_mfma_f32_16x16x32_bf16 v[16:19], v[104:107], v[116:119], v[16:19]
	v_mfma_f32_16x16x32_bf16 v[12:15], v[112:115], v[92:95], v[12:15]
	v_lshl_add_u64 v[130:131], v[70:71], 0, s[42:43]
	s_add_i32 m0, s18, 0xc00
	s_nop 0
	global_load_lds_dwordx4 v[130:131], off
	v_mfma_f32_16x16x32_bf16 v[8:11], v[112:115], v[100:103], v[8:11]
	v_lshl_add_u64 v[130:131], v[78:79], 0, s[42:43]
	s_add_i32 m0, s18, 0x4c00
	s_nop 0
	global_load_lds_dwordx4 v[130:131], off
	v_mfma_f32_16x16x32_bf16 v[4:7], v[112:115], v[108:111], v[4:7]
	v_mfma_f32_16x16x32_bf16 v[0:3], v[112:115], v[116:119], v[0:3]
	s_waitcnt vmcnt(8)
	s_barrier
	v_add_u32_e32 v132, v134, v86
	v_add_u32_e32 v133, v135, v86
	ds_read_b128 v[88:91], v132
	ds_read_b128 v[96:99], v132 offset:2048
	ds_read_b128 v[104:107], v132 offset:4096
	ds_read_b128 v[112:115], v132 offset:6144
	ds_read_b128 v[92:95], v133 offset:16384
	ds_read_b128 v[100:103], v133 offset:18432
	ds_read_b128 v[108:111], v133 offset:20480
	ds_read_b128 v[116:119], v133 offset:22528
	v_mfma_f32_16x16x32_bf16 v[60:63], v[152:155], v[168:171], v[60:63]
	v_mfma_f32_16x16x32_bf16 v[56:59], v[152:155], v[172:175], v[56:59]
	v_mfma_f32_16x16x32_bf16 v[52:55], v[152:155], v[176:179], v[52:55]
	v_mfma_f32_16x16x32_bf16 v[48:51], v[152:155], v[180:183], v[48:51]
	v_mfma_f32_16x16x32_bf16 v[44:47], v[156:159], v[168:171], v[44:47]
	v_mfma_f32_16x16x32_bf16 v[40:43], v[156:159], v[172:175], v[40:43]
	v_mfma_f32_16x16x32_bf16 v[36:39], v[156:159], v[176:179], v[36:39]
	v_mfma_f32_16x16x32_bf16 v[32:35], v[156:159], v[180:183], v[32:35]
	v_mfma_f32_16x16x32_bf16 v[28:31], v[160:163], v[168:171], v[28:31]
	v_mfma_f32_16x16x32_bf16 v[24:27], v[160:163], v[172:175], v[24:27]
	v_mfma_f32_16x16x32_bf16 v[20:23], v[160:163], v[176:179], v[20:23]
	v_mfma_f32_16x16x32_bf16 v[16:19], v[160:163], v[180:183], v[16:19]
	v_mfma_f32_16x16x32_bf16 v[12:15], v[164:167], v[168:171], v[12:15]
	v_mfma_f32_16x16x32_bf16 v[8:11], v[164:167], v[172:175], v[8:11]
	v_mfma_f32_16x16x32_bf16 v[4:7], v[164:167], v[176:179], v[4:7]
	v_mfma_f32_16x16x32_bf16 v[0:3], v[164:167], v[180:183], v[0:3]
	s_add_i32 s16, s16, 0x8000
	s_add_u32 s42, s42, 0x80
	s_addc_u32 s43, s43, 0
	s_cmpk_lg_i32 s42, 0x1580
	s_cbranch_scc1 .Lg42_loop
	s_and_b32 s17, s16, 0x8000
	s_xor_b32 s18, s17, 0x8000
	v_add_u32_e32 v132, v134, v84
	v_add_u32_e32 v133, v135, v84
	ds_read_b128 v[152:155], v132
	ds_read_b128 v[156:159], v132 offset:2048
	ds_read_b128 v[160:163], v132 offset:4096
	ds_read_b128 v[164:167], v132 offset:6144
	s_waitcnt lgkmcnt(4)
	v_mfma_f32_16x16x32_bf16 v[60:63], v[88:91], v[92:95], v[60:63]
	v_mfma_f32_16x16x32_bf16 v[56:59], v[88:91], v[100:103], v[56:59]
	v_mfma_f32_16x16x32_bf16 v[52:55], v[88:91], v[108:111], v[52:55]
	v_mfma_f32_16x16x32_bf16 v[48:51], v[88:91], v[116:119], v[48:51]
	ds_read_b128 v[168:171], v133 offset:16384
	ds_read_b128 v[172:175], v133 offset:18432
	ds_read_b128 v[176:179], v133 offset:20480
	ds_read_b128 v[180:183], v133 offset:22528
	v_mfma_f32_16x16x32_bf16 v[44:47], v[96:99], v[92:95], v[44:47]
	v_mfma_f32_16x16x32_bf16 v[40:43], v[96:99], v[100:103], v[40:43]
	v_mfma_f32_16x16x32_bf16 v[36:39], v[96:99], v[108:111], v[36:39]
	v_mfma_f32_16x16x32_bf16 v[32:35], v[96:99], v[116:119], v[32:35]
	v_mfma_f32_16x16x32_bf16 v[28:31], v[104:107], v[92:95], v[28:31]
	v_mfma_f32_16x16x32_bf16 v[24:27], v[104:107], v[100:103], v[24:27]
	v_mfma_f32_16x16x32_bf16 v[20:23], v[104:107], v[108:111], v[20:23]
	v_mfma_f32_16x16x32_bf16 v[16:19], v[104:107], v[116:119], v[16:19]
	v_mfma_f32_16x16x32_bf16 v[12:15], v[112:115], v[92:95], v[12:15]
	v_mfma_f32_16x16x32_bf16 v[8:11], v[112:115], v[100:103], v[8:11]
	v_mfma_f32_16x16x32_bf16 v[4:7], v[112:115], v[108:111], v[4:7]
	v_mfma_f32_16x16x32_bf16 v[0:3], v[112:115], v[116:119], v[0:3]
	s_waitcnt vmcnt(0) lgkmcnt(0)
	s_barrier
	v_mfma_f32_16x16x32_bf16 v[60:63], v[152:155], v[168:171], v[60:63]
	v_mfma_f32_16x16x32_bf16 v[56:59], v[152:155], v[172:175], v[56:59]
	v_mfma_f32_16x16x32_bf16 v[52:55], v[152:155], v[176:179], v[52:55]
	v_mfma_f32_16x16x32_bf16 v[48:51], v[152:155], v[180:183], v[48:51]
	v_mfma_f32_16x16x32_bf16 v[44:47], v[156:159], v[168:171], v[44:47]
	v_mfma_f32_16x16x32_bf16 v[40:43], v[156:159], v[172:175], v[40:43]
	v_mfma_f32_16x16x32_bf16 v[36:39], v[156:159], v[176:179], v[36:39]
	v_mfma_f32_16x16x32_bf16 v[32:35], v[156:159], v[180:183], v[32:35]
	v_mfma_f32_16x16x32_bf16 v[28:31], v[160:163], v[168:171], v[28:31]
	v_mfma_f32_16x16x32_bf16 v[24:27], v[160:163], v[172:175], v[24:27]
	v_mfma_f32_16x16x32_bf16 v[20:23], v[160:163], v[176:179], v[20:23]
	v_mfma_f32_16x16x32_bf16 v[16:19], v[160:163], v[180:183], v[16:19]
	v_mfma_f32_16x16x32_bf16 v[12:15], v[164:167], v[168:171], v[12:15]
	v_mfma_f32_16x16x32_bf16 v[8:11], v[164:167], v[172:175], v[8:11]
	v_mfma_f32_16x16x32_bf16 v[4:7], v[164:167], v[176:179], v[4:7]
	v_mfma_f32_16x16x32_bf16 v[0:3], v[164:167], v[180:183], v[0:3]
	v_add_u32_e32 v82, 32, v85
	v_add_u32_e32 v83, 32, v83
	v_add_u32_e32 v85, v82, v86
	ds_read_b128 v[64:67], v85 offset:32768
	v_add_u32_e32 v98, v83, v86
	ds_read_b128 v[72:75], v85 offset:34816
	ds_read_b128 v[86:89], v85 offset:36864
	ds_read_b128 v[94:97], v85 offset:38912
	ds_read_b128 v[90:93], v98 offset:53248
	ds_read_b128 v[68:71], v98 offset:49152
	ds_read_b128 v[76:79], v98 offset:51200
	ds_read_b128 v[98:101], v98 offset:55296
	s_waitcnt lgkmcnt(3)
	v_mfma_f32_16x16x32_bf16 v[52:55], v[64:67], v[90:93], v[52:55]
	s_add_i32 s3, s3, s2
	s_cmpk_gt_u32 s3, 0x7f
	v_mfma_f32_16x16x32_bf16 v[36:39], v[72:75], v[90:93], v[36:39]
	v_mfma_f32_16x16x32_bf16 v[20:23], v[86:89], v[90:93], v[20:23]
	v_mfma_f32_16x16x32_bf16 v[4:7], v[94:97], v[90:93], v[4:7]
	v_add_u32_e32 v90, v82, v84
	s_waitcnt lgkmcnt(2)
	v_mfma_f32_16x16x32_bf16 v[60:63], v[64:67], v[68:71], v[60:63]
	s_waitcnt lgkmcnt(1)
	v_mfma_f32_16x16x32_bf16 v[56:59], v[64:67], v[76:79], v[56:59]
	s_waitcnt lgkmcnt(0)
	v_mfma_f32_16x16x32_bf16 v[48:51], v[64:67], v[98:101], v[48:51]
	v_mfma_f32_16x16x32_bf16 v[44:47], v[72:75], v[68:71], v[44:47]
	v_mfma_f32_16x16x32_bf16 v[40:43], v[72:75], v[76:79], v[40:43]
	v_mfma_f32_16x16x32_bf16 v[32:35], v[72:75], v[98:101], v[32:35]
	v_mfma_f32_16x16x32_bf16 v[28:31], v[86:89], v[68:71], v[28:31]
	v_mfma_f32_16x16x32_bf16 v[24:27], v[86:89], v[76:79], v[24:27]
	v_mfma_f32_16x16x32_bf16 v[16:19], v[86:89], v[98:101], v[16:19]
	v_mfma_f32_16x16x32_bf16 v[12:15], v[94:97], v[68:71], v[12:15]
	v_mfma_f32_16x16x32_bf16 v[8:11], v[94:97], v[76:79], v[8:11]
	v_mfma_f32_16x16x32_bf16 v[0:3], v[94:97], v[98:101], v[0:3]
	ds_read_b128 v[64:67], v90 offset:32768
	v_add_u32_e32 v94, v83, v84
	ds_read_b128 v[72:75], v90 offset:34816
	ds_read_b128 v[82:85], v90 offset:36864
	ds_read_b128 v[90:93], v90 offset:38912
	ds_read_b128 v[68:71], v94 offset:49152
	ds_read_b128 v[76:79], v94 offset:51200
	ds_read_b128 v[86:89], v94 offset:53248
	ds_read_b128 v[94:97], v94 offset:55296
	s_waitcnt lgkmcnt(3)
	v_mfma_f32_16x16x32_bf16 v[60:63], v[64:67], v[68:71], v[60:63]
	s_waitcnt vmcnt(0)
	s_waitcnt lgkmcnt(0)
	s_barrier
	v_mfma_f32_16x16x32_bf16 v[56:59], v[64:67], v[76:79], v[56:59]
	s_nop 4
	v_cvt_pk_bf16_f32 v60, v60, v61
	v_cvt_pk_bf16_f32 v61, v62, v63
	v_mfma_f32_16x16x32_bf16 v[52:55], v[64:67], v[86:89], v[52:55]
	v_mfma_f32_16x16x32_bf16 v[48:51], v[64:67], v[94:97], v[48:51]
	v_and_b32_e32 v65, 0x4f, v80
	v_or_b32_e32 v66, s10, v65
	v_add_u32_e32 v64, s8, v81
	v_mfma_f32_16x16x32_bf16 v[12:15], v[90:93], v[68:71], v[12:15]
	v_ashrrev_i32_e32 v67, 31, v66
	v_ashrrev_i32_e32 v65, 31, v64
	v_lshlrev_b64 v[64:65], 1, v[64:65]
	v_mfma_f32_16x16x32_bf16 v[44:47], v[72:75], v[68:71], v[44:47]
	v_mfma_f32_16x16x32_bf16 v[28:31], v[82:85], v[68:71], v[28:31]
	v_lshlrev_b64 v[68:69], 11, v[66:67]
	v_lshl_add_u64 v[68:69], s[72:73], 0, v[68:69]
	v_lshrrev_b32_e32 v67, 1, v80
	v_lshl_add_u64 v[68:69], v[68:69], 0, v[64:65]
	v_and_b32_e32 v192, 24, v67
	v_lshl_add_u64 v[68:69], v[68:69], 0, v[192:193]
	v_cvt_pk_bf16_f32 v12, v12, v13
	v_cvt_pk_bf16_f32 v13, v14, v15
	global_store_dwordx2 v[68:69], v[12:13], off offset:96
	v_or_b32_e32 v12, 16, v66
	v_mfma_f32_16x16x32_bf16 v[8:11], v[90:93], v[76:79], v[8:11]
	v_ashrrev_i32_e32 v13, 31, v12
	v_lshlrev_b64 v[12:13], 11, v[12:13]
	v_lshl_add_u64 v[12:13], s[72:73], 0, v[12:13]
	v_lshl_add_u64 v[12:13], v[12:13], 0, v[64:65]
	v_lshl_add_u64 v[12:13], v[12:13], 0, v[192:193]
	s_nop 2
	v_cvt_pk_bf16_f32 v8, v8, v9
	v_cvt_pk_bf16_f32 v9, v10, v11
	global_store_dwordx2 v[12:13], v[8:9], off offset:96
	v_or_b32_e32 v8, 32, v66
	v_mfma_f32_16x16x32_bf16 v[4:7], v[90:93], v[86:89], v[4:7]
	v_ashrrev_i32_e32 v9, 31, v8
	v_lshlrev_b64 v[8:9], 11, v[8:9]
	v_lshl_add_u64 v[8:9], s[72:73], 0, v[8:9]
	v_lshl_add_u64 v[8:9], v[8:9], 0, v[64:65]
	v_lshl_add_u64 v[8:9], v[8:9], 0, v[192:193]
	s_nop 2
	v_cvt_pk_bf16_f32 v4, v4, v5
	v_cvt_pk_bf16_f32 v5, v6, v7
	global_store_dwordx2 v[8:9], v[4:5], off offset:96
	v_or_b32_e32 v4, 48, v66
	v_ashrrev_i32_e32 v5, 31, v4
	v_mfma_f32_16x16x32_bf16 v[40:43], v[72:75], v[76:79], v[40:43]
	v_lshlrev_b64 v[4:5], 11, v[4:5]
	v_lshl_add_u64 v[4:5], s[72:73], 0, v[4:5]
	v_lshl_add_u64 v[4:5], v[4:5], 0, v[64:65]
	v_mfma_f32_16x16x32_bf16 v[36:39], v[72:75], v[86:89], v[36:39]
	v_cvt_pk_bf16_f32 v14, v56, v57
	v_cvt_pk_bf16_f32 v15, v58, v59
	v_cvt_pk_bf16_f32 v10, v52, v53
	v_mfma_f32_16x16x32_bf16 v[32:35], v[72:75], v[94:97], v[32:35]
	v_cvt_pk_bf16_f32 v11, v54, v55
	v_lshl_add_u64 v[4:5], v[4:5], 0, v[192:193]
	v_cvt_pk_bf16_f32 v6, v48, v49
	v_mfma_f32_16x16x32_bf16 v[24:27], v[82:85], v[76:79], v[24:27]
	v_cvt_pk_bf16_f32 v7, v50, v51
	global_store_dwordx2 v[12:13], v[14:15], off
	v_cvt_pk_bf16_f32 v14, v40, v41
	v_mfma_f32_16x16x32_bf16 v[20:23], v[82:85], v[86:89], v[20:23]
	v_cvt_pk_bf16_f32 v15, v42, v43
	global_store_dwordx2 v[8:9], v[10:11], off
	v_cvt_pk_bf16_f32 v10, v36, v37
	v_mfma_f32_16x16x32_bf16 v[16:19], v[82:85], v[94:97], v[16:19]
	v_cvt_pk_bf16_f32 v11, v38, v39
	global_store_dwordx2 v[4:5], v[6:7], off
	v_cvt_pk_bf16_f32 v6, v32, v33
	v_mfma_f32_16x16x32_bf16 v[0:3], v[90:93], v[94:97], v[0:3]
	v_cvt_pk_bf16_f32 v7, v34, v35
	v_cvt_pk_bf16_f32 v44, v44, v45
	v_cvt_pk_bf16_f32 v45, v46, v47
	v_cvt_pk_bf16_f32 v28, v28, v29
	v_cvt_pk_bf16_f32 v29, v30, v31
	global_store_dwordx2 v[12:13], v[14:15], off offset:32
	v_cvt_pk_bf16_f32 v14, v24, v25
	v_cvt_pk_bf16_f32 v15, v26, v27
	global_store_dwordx2 v[8:9], v[10:11], off offset:32
	v_cvt_pk_bf16_f32 v10, v20, v21
	v_cvt_pk_bf16_f32 v11, v22, v23
	global_store_dwordx2 v[4:5], v[6:7], off offset:32
	v_cvt_pk_bf16_f32 v6, v16, v17
	v_cvt_pk_bf16_f32 v7, v18, v19
	v_cvt_pk_bf16_f32 v0, v0, v1
	v_cvt_pk_bf16_f32 v1, v2, v3
	global_store_dwordx2 v[68:69], v[60:61], off
	global_store_dwordx2 v[68:69], v[44:45], off offset:32
	global_store_dwordx2 v[68:69], v[28:29], off offset:64
	global_store_dwordx2 v[12:13], v[14:15], off offset:64
	global_store_dwordx2 v[8:9], v[10:11], off offset:64
	global_store_dwordx2 v[4:5], v[6:7], off offset:64
	global_store_dwordx2 v[4:5], v[0:1], off offset:96
	s_cbranch_scc0 .LBB0_41

.Lg65_loop:
	s_and_b32 s17, s16, 0x8000
	s_xor_b32 s18, s17, 0x8000
	v_add_u32_e32 v132, v134, v83
	v_add_u32_e32 v133, v135, v83
	ds_read_b128 v[152:155], v132
	ds_read_b128 v[156:159], v132 offset:2048
	ds_read_b128 v[160:163], v132 offset:4096
	ds_read_b128 v[164:167], v132 offset:6144
	s_waitcnt lgkmcnt(4)
	v_mfma_f32_16x16x32_bf16 v[60:63], v[88:91], v[92:95], v[60:63]
	v_mfma_f32_16x16x32_bf16 v[56:59], v[88:91], v[100:103], v[56:59]
	v_mfma_f32_16x16x32_bf16 v[52:55], v[88:91], v[108:111], v[52:55]
	v_mfma_f32_16x16x32_bf16 v[48:51], v[88:91], v[116:119], v[48:51]
	ds_read_b128 v[168:171], v133 offset:16384
	ds_read_b128 v[172:175], v133 offset:18432
	ds_read_b128 v[176:179], v133 offset:20480
	ds_read_b128 v[180:183], v133 offset:22528
	v_add_u32_e32 v128, s17, v82
	s_add_i32 s17, s18, 32
	v_add_u32_e32 v134, s17, v85
	v_add_u32_e32 v135, s17, v86
	v_readfirstlane_b32 s18, v128
	s_waitcnt lgkmcnt(0)
	s_barrier
	v_lshl_add_u64 v[130:131], v[64:65], 0, s[42:43]
	s_mov_b32 m0, s18
	s_nop 0
	global_load_lds_dwordx4 v[130:131], off
	v_mfma_f32_16x16x32_bf16 v[44:47], v[96:99], v[92:95], v[44:47]
	v_lshl_add_u64 v[130:131], v[72:73], 0, s[42:43]
	s_add_i32 m0, s18, 0x4000
	s_nop 0
	global_load_lds_dwordx4 v[130:131], off
	v_mfma_f32_16x16x32_bf16 v[40:43], v[96:99], v[100:103], v[40:43]
	v_mfma_f32_16x16x32_bf16 v[36:39], v[96:99], v[108:111], v[36:39]
	v_lshl_add_u64 v[130:131], v[66:67], 0, s[42:43]
	s_add_i32 m0, s18, 0x400
	s_nop 0
	global_load_lds_dwordx4 v[130:131], off
	v_mfma_f32_16x16x32_bf16 v[32:35], v[96:99], v[116:119], v[32:35]
	v_lshl_add_u64 v[130:131], v[74:75], 0, s[42:43]
	s_add_i32 m0, s18, 0x4400
	s_nop 0
	global_load_lds_dwordx4 v[130:131], off
	v_mfma_f32_16x16x32_bf16 v[28:31], v[104:107], v[92:95], v[28:31]
	v_mfma_f32_16x16x32_bf16 v[24:27], v[104:107], v[100:103], v[24:27]
	v_lshl_add_u64 v[130:131], v[68:69], 0, s[42:43]
	s_add_i32 m0, s18, 0x800
	s_nop 0
	global_load_lds_dwordx4 v[130:131], off
	v_mfma_f32_16x16x32_bf16 v[20:23], v[104:107], v[108:111], v[20:23]
	v_lshl_add_u64 v[130:131], v[76:77], 0, s[42:43]
	s_add_i32 m0, s18, 0x4800
	s_nop 0
	global_load_lds_dwordx4 v[130:131], off
	v_mfma_f32_16x16x32_bf16 v[16:19], v[104:107], v[116:119], v[16:19]
	v_mfma_f32_16x16x32_bf16 v[12:15], v[112:115], v[92:95], v[12:15]
	v_lshl_add_u64 v[130:131], v[70:71], 0, s[42:43]
	s_add_i32 m0, s18, 0xc00
	s_nop 0
	global_load_lds_dwordx4 v[130:131], off
	v_mfma_f32_16x16x32_bf16 v[8:11], v[112:115], v[100:103], v[8:11]
	v_lshl_add_u64 v[130:131], v[78:79], 0, s[42:43]
	s_add_i32 m0, s18, 0x4c00
	s_nop 0
	global_load_lds_dwordx4 v[130:131], off
	v_mfma_f32_16x16x32_bf16 v[4:7], v[112:115], v[108:111], v[4:7]
	v_mfma_f32_16x16x32_bf16 v[0:3], v[112:115], v[116:119], v[0:3]
	s_waitcnt vmcnt(8)
	s_barrier
	v_add_u32_e32 v132, v134, v84
	v_add_u32_e32 v133, v135, v84
	ds_read_b128 v[88:91], v132
	ds_read_b128 v[96:99], v132 offset:2048
	ds_read_b128 v[104:107], v132 offset:4096
	ds_read_b128 v[112:115], v132 offset:6144
	ds_read_b128 v[92:95], v133 offset:16384
	ds_read_b128 v[100:103], v133 offset:18432
	ds_read_b128 v[108:111], v133 offset:20480
	ds_read_b128 v[116:119], v133 offset:22528
	v_mfma_f32_16x16x32_bf16 v[60:63], v[152:155], v[168:171], v[60:63]
	v_mfma_f32_16x16x32_bf16 v[56:59], v[152:155], v[172:175], v[56:59]
	v_mfma_f32_16x16x32_bf16 v[52:55], v[152:155], v[176:179], v[52:55]
	v_mfma_f32_16x16x32_bf16 v[48:51], v[152:155], v[180:183], v[48:51]
	v_mfma_f32_16x16x32_bf16 v[44:47], v[156:159], v[168:171], v[44:47]
	v_mfma_f32_16x16x32_bf16 v[40:43], v[156:159], v[172:175], v[40:43]
	v_mfma_f32_16x16x32_bf16 v[36:39], v[156:159], v[176:179], v[36:39]
	v_mfma_f32_16x16x32_bf16 v[32:35], v[156:159], v[180:183], v[32:35]
	v_mfma_f32_16x16x32_bf16 v[28:31], v[160:163], v[168:171], v[28:31]
	v_mfma_f32_16x16x32_bf16 v[24:27], v[160:163], v[172:175], v[24:27]
	v_mfma_f32_16x16x32_bf16 v[20:23], v[160:163], v[176:179], v[20:23]
	v_mfma_f32_16x16x32_bf16 v[16:19], v[160:163], v[180:183], v[16:19]
	v_mfma_f32_16x16x32_bf16 v[12:15], v[164:167], v[168:171], v[12:15]
	v_mfma_f32_16x16x32_bf16 v[8:11], v[164:167], v[172:175], v[8:11]
	v_mfma_f32_16x16x32_bf16 v[4:7], v[164:167], v[176:179], v[4:7]
	v_mfma_f32_16x16x32_bf16 v[0:3], v[164:167], v[180:183], v[0:3]
	s_add_i32 s16, s16, 0x8000
	s_add_u32 s42, s42, 0x80
	s_addc_u32 s43, s43, 0
	s_cmpk_lg_i32 s42, 0x780
	s_cbranch_scc1 .Lg65_loop
	s_and_b32 s17, s16, 0x8000
	s_xor_b32 s18, s17, 0x8000
	v_add_u32_e32 v132, v134, v83
	v_add_u32_e32 v133, v135, v83
	ds_read_b128 v[152:155], v132
	ds_read_b128 v[156:159], v132 offset:2048
	ds_read_b128 v[160:163], v132 offset:4096
	ds_read_b128 v[164:167], v132 offset:6144
	s_waitcnt lgkmcnt(4)
	v_mfma_f32_16x16x32_bf16 v[60:63], v[88:91], v[92:95], v[60:63]
	v_mfma_f32_16x16x32_bf16 v[56:59], v[88:91], v[100:103], v[56:59]
	v_mfma_f32_16x16x32_bf16 v[52:55], v[88:91], v[108:111], v[52:55]
	v_mfma_f32_16x16x32_bf16 v[48:51], v[88:91], v[116:119], v[48:51]
	ds_read_b128 v[168:171], v133 offset:16384
	ds_read_b128 v[172:175], v133 offset:18432
	ds_read_b128 v[176:179], v133 offset:20480
	ds_read_b128 v[180:183], v133 offset:22528
	v_mfma_f32_16x16x32_bf16 v[44:47], v[96:99], v[92:95], v[44:47]
	v_mfma_f32_16x16x32_bf16 v[40:43], v[96:99], v[100:103], v[40:43]
	v_mfma_f32_16x16x32_bf16 v[36:39], v[96:99], v[108:111], v[36:39]
	v_mfma_f32_16x16x32_bf16 v[32:35], v[96:99], v[116:119], v[32:35]
	v_mfma_f32_16x16x32_bf16 v[28:31], v[104:107], v[92:95], v[28:31]
	v_mfma_f32_16x16x32_bf16 v[24:27], v[104:107], v[100:103], v[24:27]
	v_mfma_f32_16x16x32_bf16 v[20:23], v[104:107], v[108:111], v[20:23]
	v_mfma_f32_16x16x32_bf16 v[16:19], v[104:107], v[116:119], v[16:19]
	v_mfma_f32_16x16x32_bf16 v[12:15], v[112:115], v[92:95], v[12:15]
	v_mfma_f32_16x16x32_bf16 v[8:11], v[112:115], v[100:103], v[8:11]
	v_mfma_f32_16x16x32_bf16 v[4:7], v[112:115], v[108:111], v[4:7]
	v_mfma_f32_16x16x32_bf16 v[0:3], v[112:115], v[116:119], v[0:3]
	s_waitcnt vmcnt(0) lgkmcnt(0)
	s_barrier
	v_mfma_f32_16x16x32_bf16 v[60:63], v[152:155], v[168:171], v[60:63]
	v_mfma_f32_16x16x32_bf16 v[56:59], v[152:155], v[172:175], v[56:59]
	v_mfma_f32_16x16x32_bf16 v[52:55], v[152:155], v[176:179], v[52:55]
	v_mfma_f32_16x16x32_bf16 v[48:51], v[152:155], v[180:183], v[48:51]
	v_mfma_f32_16x16x32_bf16 v[44:47], v[156:159], v[168:171], v[44:47]
	v_mfma_f32_16x16x32_bf16 v[40:43], v[156:159], v[172:175], v[40:43]
	v_mfma_f32_16x16x32_bf16 v[36:39], v[156:159], v[176:179], v[36:39]
	v_mfma_f32_16x16x32_bf16 v[32:35], v[156:159], v[180:183], v[32:35]
	v_mfma_f32_16x16x32_bf16 v[28:31], v[160:163], v[168:171], v[28:31]
	v_mfma_f32_16x16x32_bf16 v[24:27], v[160:163], v[172:175], v[24:27]
	v_mfma_f32_16x16x32_bf16 v[20:23], v[160:163], v[176:179], v[20:23]
	v_mfma_f32_16x16x32_bf16 v[16:19], v[160:163], v[180:183], v[16:19]
	v_mfma_f32_16x16x32_bf16 v[12:15], v[164:167], v[168:171], v[12:15]
	v_mfma_f32_16x16x32_bf16 v[8:11], v[164:167], v[172:175], v[8:11]
	v_mfma_f32_16x16x32_bf16 v[4:7], v[164:167], v[176:179], v[4:7]
	v_mfma_f32_16x16x32_bf16 v[0:3], v[164:167], v[180:183], v[0:3]
	v_add_u32_e32 v100, 32, v85
	v_add_u32_e32 v96, v100, v84
	ds_read_b128 v[64:67], v96 offset:32768
	ds_read_b128 v[72:75], v96 offset:38912
	ds_read_b128 v[88:91], v96 offset:36864
	ds_read_b128 v[96:99], v96 offset:34816
	v_add_u32_e32 v82, 32, v86
	v_add_u32_e32 v92, v82, v84
	ds_read_b128 v[68:71], v92 offset:55296
	ds_read_b128 v[76:79], v92 offset:49152
	ds_read_b128 v[84:87], v92 offset:53248
	ds_read_b128 v[92:95], v92 offset:51200
	s_waitcnt lgkmcnt(0)
	v_mfma_f32_16x16x32_bf16 v[56:59], v[64:67], v[92:95], v[56:59]
	v_readlane_b32 s44, v252, 11
	v_readlane_b32 s45, v252, 12
	s_add_i32 s11, s11, s5
	v_mfma_f32_16x16x32_bf16 v[44:47], v[96:99], v[76:79], v[44:47]
	s_cmp_ge_u32 s11, s3
	v_readlane_b32 s46, v252, 13
	v_readlane_b32 s47, v252, 14
	v_mfma_f32_16x16x32_bf16 v[40:43], v[96:99], v[92:95], v[40:43]
	v_readlane_b32 s48, v252, 15
	v_readlane_b32 s49, v252, 16
	v_readlane_b32 s50, v252, 17
	v_mfma_f32_16x16x32_bf16 v[36:39], v[96:99], v[84:87], v[36:39]
	v_readlane_b32 s51, v252, 18
	v_mfma_f32_16x16x32_bf16 v[32:35], v[96:99], v[68:71], v[32:35]
	v_mfma_f32_16x16x32_bf16 v[96:99], v[88:91], v[92:95], v[24:27]
	v_mfma_f32_16x16x32_bf16 v[92:95], v[72:75], v[92:95], v[8:11]
	s_nop 2
	v_add_u32_e32 v8, v100, v83
	v_mfma_f32_16x16x32_bf16 v[60:63], v[64:67], v[76:79], v[60:63]
	v_add_u32_e32 v9, v82, v83
	v_mfma_f32_16x16x32_bf16 v[52:55], v[64:67], v[84:87], v[52:55]
	v_mfma_f32_16x16x32_bf16 v[48:51], v[64:67], v[68:71], v[48:51]
	v_mfma_f32_16x16x32_bf16 v[64:67], v[88:91], v[76:79], v[28:31]
	v_mfma_f32_16x16x32_bf16 v[20:23], v[88:91], v[84:87], v[20:23]
	v_mfma_f32_16x16x32_bf16 v[88:91], v[88:91], v[68:71], v[16:19]
	v_mfma_f32_16x16x32_bf16 v[76:79], v[72:75], v[76:79], v[12:15]
	v_mfma_f32_16x16x32_bf16 v[4:7], v[72:75], v[84:87], v[4:7]
	v_mfma_f32_16x16x32_bf16 v[68:71], v[72:75], v[68:71], v[0:3]
	ds_read_b128 v[72:75], v9 offset:49152
	ds_read_b128 v[12:15], v8 offset:34816
	ds_read_b128 v[100:103], v8 offset:36864
	ds_read_b128 v[0:3], v8 offset:32768
	ds_read_b128 v[108:111], v8 offset:38912
	ds_read_b128 v[104:107], v9 offset:53248
	ds_read_b128 v[112:115], v9 offset:55296
	ds_read_b128 v[82:85], v9 offset:51200
	s_waitcnt lgkmcnt(4)
	v_mfma_f32_16x16x32_bf16 v[60:63], v[0:3], v[72:75], v[60:63]
	s_waitcnt vmcnt(0)
	s_waitcnt lgkmcnt(0)
	s_barrier
	v_mfma_f32_16x16x32_bf16 v[24:27], v[0:3], v[104:107], v[52:55]
	v_mfma_f32_16x16x32_bf16 v[44:47], v[12:15], v[72:75], v[44:47]
	v_mfma_f32_16x16x32_bf16 v[28:31], v[12:15], v[104:107], v[36:39]
	v_mfma_f32_16x16x32_bf16 v[36:39], v[100:103], v[72:75], v[64:67]
	v_mfma_f32_16x16x32_bf16 v[16:19], v[100:103], v[104:107], v[20:23]
	v_mfma_f32_16x16x32_bf16 v[52:55], v[108:111], v[72:75], v[76:79]
	v_mul_f32_e32 v72, 0xbfb8aa3b, v61
	v_exp_f32_e32 v72, v72
	v_mul_f32_e32 v73, 0xbfb8aa3b, v63
	v_mfma_f32_16x16x32_bf16 v[20:23], v[108:111], v[104:107], v[4:7]
	v_exp_f32_e32 v73, v73
	s_nop 0
	v_add_f32_e32 v73, 1.0, v73
	v_mfma_f32_16x16x32_bf16 v[4:7], v[108:111], v[112:115], v[68:71]
	v_rcp_f32_e32 v73, v73
	s_nop 1
	v_mul_f32_e32 v71, 0xbfb8aa3b, v60
	v_exp_f32_e32 v71, v71
	v_lshrrev_b32_e32 v70, 1, v80
	v_and_b32_e32 v192, 24, v70
	v_mfma_f32_16x16x32_bf16 v[56:59], v[0:3], v[82:85], v[56:59]
	v_add_f32_e32 v70, 1.0, v71
	v_add_f32_e32 v71, 1.0, v72
	v_mul_f32_e32 v72, 0xbfb8aa3b, v62
	v_exp_f32_e32 v72, v72
	v_rcp_f32_e32 v70, v70
	v_rcp_f32_e32 v71, v71
	v_mfma_f32_16x16x32_bf16 v[40:43], v[12:15], v[82:85], v[40:43]
	v_add_f32_e32 v72, 1.0, v72
	v_rcp_f32_e32 v72, v72
	v_pk_mul_f32 v[60:61], v[60:61], v[70:71]
	v_mfma_f32_16x16x32_bf16 v[12:15], v[12:15], v[112:115], v[32:35]
	v_mul_f32_e64 v44, v44, v60
	v_mul_f32_e64 v45, v45, v61
	v_pk_mul_f32 v[60:61], v[62:63], v[72:73]
	v_cvt_pk_bf16_f32 v44, v44, v45
	v_mul_f32_e32 v45, 0xbfb8aa3b, v36
	v_pk_mul_f32 v[46:47], v[46:47], v[60:61]
	v_exp_f32_e32 v60, v45
	v_mul_f32_e32 v45, 0xbfb8aa3b, v37
	v_exp_f32_e32 v61, v45
	v_cvt_pk_bf16_f32 v45, v46, v47
	v_add_f32_e32 v46, 1.0, v60
	v_mul_f32_e32 v60, 0xbfb8aa3b, v38
	v_add_f32_e32 v47, 1.0, v61
	v_mul_f32_e32 v61, 0xbfb8aa3b, v39
	v_exp_f32_e32 v60, v60
	v_exp_f32_e32 v61, v61
	v_rcp_f32_e32 v46, v46
	v_rcp_f32_e32 v47, v47
	v_add_f32_e32 v60, 1.0, v60
	v_add_f32_e32 v61, 1.0, v61
	v_rcp_f32_e32 v60, v60
	v_rcp_f32_e32 v61, v61
	v_add_u32_e32 v32, s8, v81
	v_and_b32_e32 v33, 0x4f, v80
	v_ashrrev_i32_e32 v32, 1, v32
	v_or_b32_e32 v74, s12, v33
	v_ashrrev_i32_e32 v33, 31, v32
	v_mov_b64_e32 v[34:35], s[44:45]
	s_movk_i32 s8, 0x1600
	v_pk_mul_f32 v[36:37], v[36:37], v[46:47]
	v_pk_mul_f32 v[38:39], v[38:39], v[60:61]
	v_mad_i64_i32 v[68:69], s[16:17], v74, s8, v[34:35]
	v_lshlrev_b64 v[32:33], 1, v[32:33]
	v_pk_mul_f32 v[36:37], v[52:53], v[36:37]
	v_pk_mul_f32 v[38:39], v[54:55], v[38:39]
	v_lshl_add_u64 v[68:69], v[68:69], 0, v[32:33]
	v_cvt_pk_bf16_f32 v36, v36, v37
	v_cvt_pk_bf16_f32 v37, v38, v39
	v_mul_f32_e32 v38, 0xbfb8aa3b, v56
	v_mul_f32_e32 v39, 0xbfb8aa3b, v57
	v_lshl_add_u64 v[68:69], v[68:69], 0, v[192:193]
	v_exp_f32_e32 v38, v38
	v_exp_f32_e32 v39, v39
	global_store_dwordx2 v[68:69], v[44:45], off
	v_mul_f32_e32 v44, 0xbfb8aa3b, v58
	v_mul_f32_e32 v45, 0xbfb8aa3b, v59
	v_exp_f32_e32 v44, v44
	v_exp_f32_e32 v45, v45
	v_add_f32_e32 v38, 1.0, v38
	v_add_f32_e32 v39, 1.0, v39
	v_rcp_f32_e32 v38, v38
	v_rcp_f32_e32 v39, v39
	v_add_f32_e32 v44, 1.0, v44
	v_add_f32_e32 v45, 1.0, v45
	v_mfma_f32_16x16x32_bf16 v[8:11], v[0:3], v[112:115], v[48:51]
	v_rcp_f32_e32 v44, v44
	v_rcp_f32_e32 v45, v45
	v_pk_mul_f32 v[38:39], v[56:57], v[38:39]
	v_mfma_f32_16x16x32_bf16 v[48:51], v[100:103], v[82:85], v[96:99]
	v_mul_f32_e64 v38, v40, v38
	v_mul_f32_e64 v39, v41, v39
	v_pk_mul_f32 v[40:41], v[58:59], v[44:45]
	v_cvt_pk_bf16_f32 v38, v38, v39
	v_pk_mul_f32 v[40:41], v[42:43], v[40:41]
	global_store_dwordx2 v[68:69], v[36:37], off offset:32
	s_nop 1
	v_mul_f32_e32 v39, 0xbfb8aa3b, v48
	v_exp_f32_e32 v42, v39
	v_mul_f32_e32 v39, 0xbfb8aa3b, v49
	v_exp_f32_e32 v43, v39
	v_cvt_pk_bf16_f32 v39, v40, v41
	v_add_f32_e32 v40, 1.0, v42
	v_mul_f32_e32 v42, 0xbfb8aa3b, v50
	v_add_f32_e32 v41, 1.0, v43
	v_mul_f32_e32 v43, 0xbfb8aa3b, v51
	v_exp_f32_e32 v42, v42
	v_exp_f32_e32 v43, v43
	v_or_b32_e32 v36, 16, v74
	v_rcp_f32_e32 v40, v40
	v_add_f32_e32 v42, 1.0, v42
	v_add_f32_e32 v43, 1.0, v43
	v_rcp_f32_e32 v41, v41
	v_rcp_f32_e32 v42, v42
	v_rcp_f32_e32 v43, v43
	v_mfma_f32_16x16x32_bf16 v[64:67], v[108:111], v[82:85], v[92:95]
	v_mad_i64_i32 v[36:37], s[16:17], v36, s8, v[34:35]
	v_lshl_add_u64 v[36:37], v[36:37], 0, v[32:33]
	v_lshl_add_u64 v[36:37], v[36:37], 0, v[192:193]
	global_store_dwordx2 v[36:37], v[38:39], off
	v_pk_mul_f32 v[38:39], v[48:49], v[40:41]
	v_pk_mul_f32 v[40:41], v[50:51], v[42:43]
	s_nop 1
	v_pk_mul_f32 v[38:39], v[64:65], v[38:39]
	v_pk_mul_f32 v[40:41], v[66:67], v[40:41]
	v_cvt_pk_bf16_f32 v38, v38, v39
	v_cvt_pk_bf16_f32 v39, v40, v41
	global_store_dwordx2 v[36:37], v[38:39], off offset:32
	v_mul_f32_e32 v38, 0xbfb8aa3b, v24
	v_mul_f32_e32 v39, 0xbfb8aa3b, v25
	v_exp_f32_e32 v38, v38
	v_exp_f32_e32 v39, v39
	v_mul_f32_e32 v40, 0xbfb8aa3b, v26
	v_mul_f32_e32 v41, 0xbfb8aa3b, v27
	v_add_f32_e32 v38, 1.0, v38
	v_add_f32_e32 v39, 1.0, v39
	v_rcp_f32_e32 v38, v38
	v_rcp_f32_e32 v39, v39
	v_exp_f32_e32 v40, v40
	v_exp_f32_e32 v41, v41
	v_mfma_f32_16x16x32_bf16 v[0:3], v[100:103], v[112:115], v[88:91]
	v_mul_f32_e64 v24, v24, v38
	v_mul_f32_e64 v25, v25, v39
	v_add_f32_e32 v40, 1.0, v40
	v_add_f32_e32 v41, 1.0, v41
	v_pk_mul_f32 v[24:25], v[28:29], v[24:25]
	v_rcp_f32_e32 v40, v40
	v_rcp_f32_e32 v41, v41
	v_cvt_pk_bf16_f32 v24, v24, v25
	v_mul_f32_e32 v25, 0xbfb8aa3b, v16
	v_exp_f32_e32 v28, v25
	v_mul_f32_e32 v25, 0xbfb8aa3b, v17
	v_exp_f32_e32 v29, v25
	v_pk_mul_f32 v[26:27], v[26:27], v[40:41]
	v_or_b32_e32 v36, 32, v74
	v_pk_mul_f32 v[26:27], v[30:31], v[26:27]
	v_mad_i64_i32 v[36:37], s[16:17], v36, s8, v[34:35]
	v_cvt_pk_bf16_f32 v25, v26, v27
	v_add_f32_e32 v26, 1.0, v28
	v_add_f32_e32 v27, 1.0, v29
	v_mul_f32_e32 v28, 0xbfb8aa3b, v18
	v_mul_f32_e32 v29, 0xbfb8aa3b, v19
	v_exp_f32_e32 v28, v28
	v_exp_f32_e32 v29, v29
	v_rcp_f32_e32 v26, v26
	v_rcp_f32_e32 v27, v27
	v_add_f32_e32 v28, 1.0, v28
	v_add_f32_e32 v29, 1.0, v29
	v_rcp_f32_e32 v28, v28
	v_rcp_f32_e32 v29, v29
	v_pk_mul_f32 v[16:17], v[16:17], v[26:27]
	v_lshl_add_u64 v[36:37], v[36:37], 0, v[32:33]
	v_pk_mul_f32 v[16:17], v[20:21], v[16:17]
	v_pk_mul_f32 v[18:19], v[18:19], v[28:29]
	v_cvt_pk_bf16_f32 v16, v16, v17
	v_pk_mul_f32 v[18:19], v[22:23], v[18:19]
	v_mul_f32_e32 v20, 0xbfb8aa3b, v10
	v_cvt_pk_bf16_f32 v17, v18, v19
	v_mul_f32_e32 v18, 0xbfb8aa3b, v8
	v_mul_f32_e32 v19, 0xbfb8aa3b, v9
	v_exp_f32_e32 v18, v18
	v_exp_f32_e32 v19, v19
	v_mul_f32_e32 v21, 0xbfb8aa3b, v11
	v_exp_f32_e32 v20, v20
	v_add_f32_e32 v18, 1.0, v18
	v_add_f32_e32 v19, 1.0, v19
	v_rcp_f32_e32 v18, v18
	v_rcp_f32_e32 v19, v19
	v_exp_f32_e32 v21, v21
	v_add_f32_e32 v20, 1.0, v20
	v_rcp_f32_e32 v20, v20
	v_pk_mul_f32 v[8:9], v[8:9], v[18:19]
	v_add_f32_e32 v21, 1.0, v21
	v_pk_mul_f32 v[8:9], v[12:13], v[8:9]
	v_rcp_f32_e32 v21, v21
	v_cvt_pk_bf16_f32 v8, v8, v9
	v_mul_f32_e32 v9, 0xbfb8aa3b, v0
	v_exp_f32_e32 v12, v9
	v_mul_f32_e32 v9, 0xbfb8aa3b, v1
	v_exp_f32_e32 v13, v9
	v_pk_mul_f32 v[10:11], v[10:11], v[20:21]
	v_lshl_add_u64 v[36:37], v[36:37], 0, v[192:193]
	v_pk_mul_f32 v[10:11], v[14:15], v[10:11]
	global_store_dwordx2 v[36:37], v[16:17], off offset:32
	v_cvt_pk_bf16_f32 v9, v10, v11
	v_add_f32_e32 v10, 1.0, v12
	v_add_f32_e32 v11, 1.0, v13
	v_mul_f32_e32 v12, 0xbfb8aa3b, v2
	v_mul_f32_e32 v13, 0xbfb8aa3b, v3
	v_exp_f32_e32 v12, v12
	v_exp_f32_e32 v13, v13
	v_rcp_f32_e32 v10, v10
	v_rcp_f32_e32 v11, v11
	v_add_f32_e32 v12, 1.0, v12
	v_add_f32_e32 v13, 1.0, v13
	v_rcp_f32_e32 v12, v12
	v_rcp_f32_e32 v13, v13
	v_or_b32_e32 v16, 48, v74
	v_mad_i64_i32 v[16:17], s[16:17], v16, s8, v[34:35]
	v_pk_mul_f32 v[0:1], v[0:1], v[10:11]
	v_pk_mul_f32 v[2:3], v[2:3], v[12:13]
	v_lshl_add_u64 v[16:17], v[16:17], 0, v[32:33]
	v_pk_mul_f32 v[0:1], v[4:5], v[0:1]
	v_pk_mul_f32 v[2:3], v[6:7], v[2:3]
	v_lshl_add_u64 v[16:17], v[16:17], 0, v[192:193]
	v_cvt_pk_bf16_f32 v0, v0, v1
	v_cvt_pk_bf16_f32 v1, v2, v3
	global_store_dwordx2 v[36:37], v[24:25], off
	global_store_dwordx2 v[16:17], v[8:9], off
	global_store_dwordx2 v[16:17], v[0:1], off offset:32
	s_cbranch_scc0 .LBB0_62

.Lg80_loop:
	s_and_b32 s12, s11, 0x8000
	s_xor_b32 s16, s12, 0x8000
	v_add_u32_e32 v132, v134, v84
	v_add_u32_e32 v133, v135, v84
	ds_read_b128 v[152:155], v132
	ds_read_b128 v[156:159], v132 offset:2048
	ds_read_b128 v[160:163], v132 offset:4096
	ds_read_b128 v[164:167], v132 offset:6144
	s_waitcnt lgkmcnt(4)
	v_mfma_f32_16x16x32_bf16 v[60:63], v[88:91], v[92:95], v[60:63]
	v_mfma_f32_16x16x32_bf16 v[56:59], v[88:91], v[100:103], v[56:59]
	v_mfma_f32_16x16x32_bf16 v[52:55], v[88:91], v[108:111], v[52:55]
	v_mfma_f32_16x16x32_bf16 v[48:51], v[88:91], v[116:119], v[48:51]
	ds_read_b128 v[168:171], v133 offset:16384
	ds_read_b128 v[172:175], v133 offset:18432
	ds_read_b128 v[176:179], v133 offset:20480
	ds_read_b128 v[180:183], v133 offset:22528
	v_add_u32_e32 v128, s12, v82
	s_add_i32 s12, s16, 32
	v_add_u32_e32 v134, s12, v85
	v_add_u32_e32 v135, s12, v83
	v_readfirstlane_b32 s16, v128
	s_waitcnt lgkmcnt(0)
	s_barrier
	v_lshl_add_u64 v[130:131], v[64:65], 0, s[40:41]
	s_mov_b32 m0, s16
	s_nop 0
	global_load_lds_dwordx4 v[130:131], off
	v_mfma_f32_16x16x32_bf16 v[44:47], v[96:99], v[92:95], v[44:47]
	v_lshl_add_u64 v[130:131], v[72:73], 0, s[40:41]
	s_add_i32 m0, s16, 0x4000
	s_nop 0
	global_load_lds_dwordx4 v[130:131], off
	v_mfma_f32_16x16x32_bf16 v[40:43], v[96:99], v[100:103], v[40:43]
	v_mfma_f32_16x16x32_bf16 v[36:39], v[96:99], v[108:111], v[36:39]
	v_lshl_add_u64 v[130:131], v[66:67], 0, s[40:41]
	s_add_i32 m0, s16, 0x400
	s_nop 0
	global_load_lds_dwordx4 v[130:131], off
	v_mfma_f32_16x16x32_bf16 v[32:35], v[96:99], v[116:119], v[32:35]
	v_lshl_add_u64 v[130:131], v[74:75], 0, s[40:41]
	s_add_i32 m0, s16, 0x4400
	s_nop 0
	global_load_lds_dwordx4 v[130:131], off
	v_mfma_f32_16x16x32_bf16 v[28:31], v[104:107], v[92:95], v[28:31]
	v_mfma_f32_16x16x32_bf16 v[24:27], v[104:107], v[100:103], v[24:27]
	v_lshl_add_u64 v[130:131], v[68:69], 0, s[40:41]
	s_add_i32 m0, s16, 0x800
	s_nop 0
	global_load_lds_dwordx4 v[130:131], off
	v_mfma_f32_16x16x32_bf16 v[20:23], v[104:107], v[108:111], v[20:23]
	v_lshl_add_u64 v[130:131], v[76:77], 0, s[40:41]
	s_add_i32 m0, s16, 0x4800
	s_nop 0
	global_load_lds_dwordx4 v[130:131], off
	v_mfma_f32_16x16x32_bf16 v[16:19], v[104:107], v[116:119], v[16:19]
	v_mfma_f32_16x16x32_bf16 v[12:15], v[112:115], v[92:95], v[12:15]
	v_lshl_add_u64 v[130:131], v[70:71], 0, s[40:41]
	s_add_i32 m0, s16, 0xc00
	s_nop 0
	global_load_lds_dwordx4 v[130:131], off
	v_mfma_f32_16x16x32_bf16 v[8:11], v[112:115], v[100:103], v[8:11]
	v_lshl_add_u64 v[130:131], v[78:79], 0, s[40:41]
	s_add_i32 m0, s16, 0x4c00
	s_nop 0
	global_load_lds_dwordx4 v[130:131], off
	v_mfma_f32_16x16x32_bf16 v[4:7], v[112:115], v[108:111], v[4:7]
	v_mfma_f32_16x16x32_bf16 v[0:3], v[112:115], v[116:119], v[0:3]
	s_waitcnt vmcnt(8)
	s_barrier
	v_add_u32_e32 v132, v134, v86
	v_add_u32_e32 v133, v135, v86
	ds_read_b128 v[88:91], v132
	ds_read_b128 v[96:99], v132 offset:2048
	ds_read_b128 v[104:107], v132 offset:4096
	ds_read_b128 v[112:115], v132 offset:6144
	ds_read_b128 v[92:95], v133 offset:16384
	ds_read_b128 v[100:103], v133 offset:18432
	ds_read_b128 v[108:111], v133 offset:20480
	ds_read_b128 v[116:119], v133 offset:22528
	v_mfma_f32_16x16x32_bf16 v[60:63], v[152:155], v[168:171], v[60:63]
	v_mfma_f32_16x16x32_bf16 v[56:59], v[152:155], v[172:175], v[56:59]
	v_mfma_f32_16x16x32_bf16 v[52:55], v[152:155], v[176:179], v[52:55]
	v_mfma_f32_16x16x32_bf16 v[48:51], v[152:155], v[180:183], v[48:51]
	v_mfma_f32_16x16x32_bf16 v[44:47], v[156:159], v[168:171], v[44:47]
	v_mfma_f32_16x16x32_bf16 v[40:43], v[156:159], v[172:175], v[40:43]
	v_mfma_f32_16x16x32_bf16 v[36:39], v[156:159], v[176:179], v[36:39]
	v_mfma_f32_16x16x32_bf16 v[32:35], v[156:159], v[180:183], v[32:35]
	v_mfma_f32_16x16x32_bf16 v[28:31], v[160:163], v[168:171], v[28:31]
	v_mfma_f32_16x16x32_bf16 v[24:27], v[160:163], v[172:175], v[24:27]
	v_mfma_f32_16x16x32_bf16 v[20:23], v[160:163], v[176:179], v[20:23]
	v_mfma_f32_16x16x32_bf16 v[16:19], v[160:163], v[180:183], v[16:19]
	v_mfma_f32_16x16x32_bf16 v[12:15], v[164:167], v[168:171], v[12:15]
	v_mfma_f32_16x16x32_bf16 v[8:11], v[164:167], v[172:175], v[8:11]
	v_mfma_f32_16x16x32_bf16 v[4:7], v[164:167], v[176:179], v[4:7]
	v_mfma_f32_16x16x32_bf16 v[0:3], v[164:167], v[180:183], v[0:3]
	s_add_i32 s11, s11, 0x8000
	s_add_u32 s40, s40, 0x80
	s_addc_u32 s41, s41, 0
	s_cmpk_lg_i32 s40, 0x780
	s_cbranch_scc1 .Lg80_loop
	s_and_b32 s12, s11, 0x8000
	s_xor_b32 s16, s12, 0x8000
	v_add_u32_e32 v132, v134, v84
	v_add_u32_e32 v133, v135, v84
	ds_read_b128 v[152:155], v132
	ds_read_b128 v[156:159], v132 offset:2048
	ds_read_b128 v[160:163], v132 offset:4096
	ds_read_b128 v[164:167], v132 offset:6144
	s_waitcnt lgkmcnt(4)
	v_mfma_f32_16x16x32_bf16 v[60:63], v[88:91], v[92:95], v[60:63]
	v_mfma_f32_16x16x32_bf16 v[56:59], v[88:91], v[100:103], v[56:59]
	v_mfma_f32_16x16x32_bf16 v[52:55], v[88:91], v[108:111], v[52:55]
	v_mfma_f32_16x16x32_bf16 v[48:51], v[88:91], v[116:119], v[48:51]
	ds_read_b128 v[168:171], v133 offset:16384
	ds_read_b128 v[172:175], v133 offset:18432
	ds_read_b128 v[176:179], v133 offset:20480
	ds_read_b128 v[180:183], v133 offset:22528
	v_mfma_f32_16x16x32_bf16 v[44:47], v[96:99], v[92:95], v[44:47]
	v_mfma_f32_16x16x32_bf16 v[40:43], v[96:99], v[100:103], v[40:43]
	v_mfma_f32_16x16x32_bf16 v[36:39], v[96:99], v[108:111], v[36:39]
	v_mfma_f32_16x16x32_bf16 v[32:35], v[96:99], v[116:119], v[32:35]
	v_mfma_f32_16x16x32_bf16 v[28:31], v[104:107], v[92:95], v[28:31]
	v_mfma_f32_16x16x32_bf16 v[24:27], v[104:107], v[100:103], v[24:27]
	v_mfma_f32_16x16x32_bf16 v[20:23], v[104:107], v[108:111], v[20:23]
	v_mfma_f32_16x16x32_bf16 v[16:19], v[104:107], v[116:119], v[16:19]
	v_mfma_f32_16x16x32_bf16 v[12:15], v[112:115], v[92:95], v[12:15]
	v_mfma_f32_16x16x32_bf16 v[8:11], v[112:115], v[100:103], v[8:11]
	v_mfma_f32_16x16x32_bf16 v[4:7], v[112:115], v[108:111], v[4:7]
	v_mfma_f32_16x16x32_bf16 v[0:3], v[112:115], v[116:119], v[0:3]
	s_waitcnt vmcnt(0) lgkmcnt(0)
	s_barrier
	v_mfma_f32_16x16x32_bf16 v[60:63], v[152:155], v[168:171], v[60:63]
	v_mfma_f32_16x16x32_bf16 v[56:59], v[152:155], v[172:175], v[56:59]
	v_mfma_f32_16x16x32_bf16 v[52:55], v[152:155], v[176:179], v[52:55]
	v_mfma_f32_16x16x32_bf16 v[48:51], v[152:155], v[180:183], v[48:51]
	v_mfma_f32_16x16x32_bf16 v[44:47], v[156:159], v[168:171], v[44:47]
	v_mfma_f32_16x16x32_bf16 v[40:43], v[156:159], v[172:175], v[40:43]
	v_mfma_f32_16x16x32_bf16 v[36:39], v[156:159], v[176:179], v[36:39]
	v_mfma_f32_16x16x32_bf16 v[32:35], v[156:159], v[180:183], v[32:35]
	v_mfma_f32_16x16x32_bf16 v[28:31], v[160:163], v[168:171], v[28:31]
	v_mfma_f32_16x16x32_bf16 v[24:27], v[160:163], v[172:175], v[24:27]
	v_mfma_f32_16x16x32_bf16 v[20:23], v[160:163], v[176:179], v[20:23]
	v_mfma_f32_16x16x32_bf16 v[16:19], v[160:163], v[180:183], v[16:19]
	v_mfma_f32_16x16x32_bf16 v[12:15], v[164:167], v[168:171], v[12:15]
	v_mfma_f32_16x16x32_bf16 v[8:11], v[164:167], v[172:175], v[8:11]
	v_mfma_f32_16x16x32_bf16 v[4:7], v[164:167], v[176:179], v[4:7]
	v_mfma_f32_16x16x32_bf16 v[0:3], v[164:167], v[180:183], v[0:3]
	v_add_u32_e32 v82, 32, v85
	v_add_u32_e32 v83, 32, v83
	v_add_u32_e32 v85, v82, v86
	ds_read_b128 v[64:67], v85 offset:32768
	v_add_u32_e32 v98, v83, v86
	ds_read_b128 v[72:75], v85 offset:34816
	ds_read_b128 v[86:89], v85 offset:36864
	ds_read_b128 v[94:97], v85 offset:38912
	ds_read_b128 v[90:93], v98 offset:53248
	ds_read_b128 v[68:71], v98 offset:49152
	ds_read_b128 v[76:79], v98 offset:51200
	ds_read_b128 v[98:101], v98 offset:55296
	s_waitcnt lgkmcnt(3)
	v_mfma_f32_16x16x32_bf16 v[52:55], v[64:67], v[90:93], v[52:55]
	s_add_i32 s2, s2, s8
	s_cmpk_gt_u32 s2, 0x7f
	v_mfma_f32_16x16x32_bf16 v[36:39], v[72:75], v[90:93], v[36:39]
	v_mfma_f32_16x16x32_bf16 v[20:23], v[86:89], v[90:93], v[20:23]
	v_mfma_f32_16x16x32_bf16 v[4:7], v[94:97], v[90:93], v[4:7]
	v_add_u32_e32 v90, v82, v84
	s_waitcnt lgkmcnt(2)
	v_mfma_f32_16x16x32_bf16 v[60:63], v[64:67], v[68:71], v[60:63]
	s_waitcnt lgkmcnt(1)
	v_mfma_f32_16x16x32_bf16 v[56:59], v[64:67], v[76:79], v[56:59]
	s_waitcnt lgkmcnt(0)
	v_mfma_f32_16x16x32_bf16 v[48:51], v[64:67], v[98:101], v[48:51]
	v_mfma_f32_16x16x32_bf16 v[44:47], v[72:75], v[68:71], v[44:47]
	v_mfma_f32_16x16x32_bf16 v[40:43], v[72:75], v[76:79], v[40:43]
	v_mfma_f32_16x16x32_bf16 v[32:35], v[72:75], v[98:101], v[32:35]
	v_mfma_f32_16x16x32_bf16 v[28:31], v[86:89], v[68:71], v[28:31]
	v_mfma_f32_16x16x32_bf16 v[24:27], v[86:89], v[76:79], v[24:27]
	v_mfma_f32_16x16x32_bf16 v[16:19], v[86:89], v[98:101], v[16:19]
	v_mfma_f32_16x16x32_bf16 v[12:15], v[94:97], v[68:71], v[12:15]
	v_mfma_f32_16x16x32_bf16 v[8:11], v[94:97], v[76:79], v[8:11]
	v_mfma_f32_16x16x32_bf16 v[0:3], v[94:97], v[98:101], v[0:3]
	ds_read_b128 v[64:67], v90 offset:32768
	v_add_u32_e32 v94, v83, v84
	ds_read_b128 v[72:75], v90 offset:34816
	ds_read_b128 v[82:85], v90 offset:36864
	ds_read_b128 v[90:93], v90 offset:38912
	ds_read_b128 v[68:71], v94 offset:49152
	ds_read_b128 v[76:79], v94 offset:51200
	ds_read_b128 v[86:89], v94 offset:53248
	ds_read_b128 v[94:97], v94 offset:55296
	s_waitcnt lgkmcnt(3)
	v_mfma_f32_16x16x32_bf16 v[60:63], v[64:67], v[68:71], v[60:63]
	s_waitcnt vmcnt(0)
	s_waitcnt lgkmcnt(0)
	s_barrier
	v_mfma_f32_16x16x32_bf16 v[56:59], v[64:67], v[76:79], v[56:59]
	s_nop 4
	v_cvt_pk_bf16_f32 v60, v60, v61
	v_cvt_pk_bf16_f32 v61, v62, v63
	v_mfma_f32_16x16x32_bf16 v[52:55], v[64:67], v[86:89], v[52:55]
	v_mfma_f32_16x16x32_bf16 v[48:51], v[64:67], v[94:97], v[48:51]
	v_and_b32_e32 v65, 0x4f, v80
	v_or_b32_e32 v66, s10, v65
	v_add_u32_e32 v64, s3, v81
	v_mfma_f32_16x16x32_bf16 v[12:15], v[90:93], v[68:71], v[12:15]
	v_ashrrev_i32_e32 v67, 31, v66
	v_ashrrev_i32_e32 v65, 31, v64
	v_lshlrev_b64 v[64:65], 1, v[64:65]
	v_mfma_f32_16x16x32_bf16 v[44:47], v[72:75], v[68:71], v[44:47]
	v_mfma_f32_16x16x32_bf16 v[28:31], v[82:85], v[68:71], v[28:31]
	v_lshlrev_b64 v[68:69], 11, v[66:67]
	v_lshl_add_u64 v[68:69], s[72:73], 0, v[68:69]
	v_lshrrev_b32_e32 v67, 1, v80
	v_lshl_add_u64 v[68:69], v[68:69], 0, v[64:65]
	v_and_b32_e32 v192, 24, v67
	v_lshl_add_u64 v[68:69], v[68:69], 0, v[192:193]
	v_cvt_pk_bf16_f32 v12, v12, v13
	v_cvt_pk_bf16_f32 v13, v14, v15
	global_store_dwordx2 v[68:69], v[12:13], off offset:96
	v_or_b32_e32 v12, 16, v66
	v_mfma_f32_16x16x32_bf16 v[8:11], v[90:93], v[76:79], v[8:11]
	v_ashrrev_i32_e32 v13, 31, v12
	v_lshlrev_b64 v[12:13], 11, v[12:13]
	v_lshl_add_u64 v[12:13], s[72:73], 0, v[12:13]
	v_lshl_add_u64 v[12:13], v[12:13], 0, v[64:65]
	v_lshl_add_u64 v[12:13], v[12:13], 0, v[192:193]
	s_nop 2
	v_cvt_pk_bf16_f32 v8, v8, v9
	v_cvt_pk_bf16_f32 v9, v10, v11
	global_store_dwordx2 v[12:13], v[8:9], off offset:96
	v_or_b32_e32 v8, 32, v66
	v_mfma_f32_16x16x32_bf16 v[4:7], v[90:93], v[86:89], v[4:7]
	v_ashrrev_i32_e32 v9, 31, v8
	v_lshlrev_b64 v[8:9], 11, v[8:9]
	v_lshl_add_u64 v[8:9], s[72:73], 0, v[8:9]
	v_lshl_add_u64 v[8:9], v[8:9], 0, v[64:65]
	v_lshl_add_u64 v[8:9], v[8:9], 0, v[192:193]
	s_nop 2
	v_cvt_pk_bf16_f32 v4, v4, v5
	v_cvt_pk_bf16_f32 v5, v6, v7
	global_store_dwordx2 v[8:9], v[4:5], off offset:96
	v_or_b32_e32 v4, 48, v66
	v_ashrrev_i32_e32 v5, 31, v4
	v_mfma_f32_16x16x32_bf16 v[40:43], v[72:75], v[76:79], v[40:43]
	v_lshlrev_b64 v[4:5], 11, v[4:5]
	v_lshl_add_u64 v[4:5], s[72:73], 0, v[4:5]
	v_lshl_add_u64 v[4:5], v[4:5], 0, v[64:65]
	v_mfma_f32_16x16x32_bf16 v[36:39], v[72:75], v[86:89], v[36:39]
	v_cvt_pk_bf16_f32 v14, v56, v57
	v_cvt_pk_bf16_f32 v15, v58, v59
	v_cvt_pk_bf16_f32 v10, v52, v53
	v_mfma_f32_16x16x32_bf16 v[32:35], v[72:75], v[94:97], v[32:35]
	v_cvt_pk_bf16_f32 v11, v54, v55
	v_lshl_add_u64 v[4:5], v[4:5], 0, v[192:193]
	v_cvt_pk_bf16_f32 v6, v48, v49
	v_mfma_f32_16x16x32_bf16 v[24:27], v[82:85], v[76:79], v[24:27]
	v_cvt_pk_bf16_f32 v7, v50, v51
	global_store_dwordx2 v[12:13], v[14:15], off
	v_cvt_pk_bf16_f32 v14, v40, v41
	v_mfma_f32_16x16x32_bf16 v[20:23], v[82:85], v[86:89], v[20:23]
	v_cvt_pk_bf16_f32 v15, v42, v43
	global_store_dwordx2 v[8:9], v[10:11], off
	v_cvt_pk_bf16_f32 v10, v36, v37
	v_mfma_f32_16x16x32_bf16 v[16:19], v[82:85], v[94:97], v[16:19]
	v_cvt_pk_bf16_f32 v11, v38, v39
	global_store_dwordx2 v[4:5], v[6:7], off
	v_cvt_pk_bf16_f32 v6, v32, v33
	v_mfma_f32_16x16x32_bf16 v[0:3], v[90:93], v[94:97], v[0:3]
	v_cvt_pk_bf16_f32 v7, v34, v35
	v_cvt_pk_bf16_f32 v44, v44, v45
	v_cvt_pk_bf16_f32 v45, v46, v47
	v_cvt_pk_bf16_f32 v28, v28, v29
	v_cvt_pk_bf16_f32 v29, v30, v31
	global_store_dwordx2 v[12:13], v[14:15], off offset:32
	v_cvt_pk_bf16_f32 v14, v24, v25
	v_cvt_pk_bf16_f32 v15, v26, v27
	global_store_dwordx2 v[8:9], v[10:11], off offset:32
	v_cvt_pk_bf16_f32 v10, v20, v21
	v_cvt_pk_bf16_f32 v11, v22, v23
	global_store_dwordx2 v[4:5], v[6:7], off offset:32
	v_cvt_pk_bf16_f32 v6, v16, v17
	v_cvt_pk_bf16_f32 v7, v18, v19
	v_cvt_pk_bf16_f32 v0, v0, v1
	v_cvt_pk_bf16_f32 v1, v2, v3
	global_store_dwordx2 v[68:69], v[60:61], off
	global_store_dwordx2 v[68:69], v[44:45], off offset:32
	global_store_dwordx2 v[68:69], v[28:29], off offset:64
	global_store_dwordx2 v[12:13], v[14:15], off offset:64
	global_store_dwordx2 v[8:9], v[10:11], off offset:64
	global_store_dwordx2 v[4:5], v[6:7], off offset:64
	global_store_dwordx2 v[4:5], v[0:1], off offset:96
	s_cbranch_scc0 .LBB0_79

.Lg255_loop:
	s_and_b32 s10, s8, 0x8000
	s_xor_b32 s12, s10, 0x8000
	v_add_u32_e32 v132, v134, v86
	v_add_u32_e32 v133, v135, v86
	ds_read_b128 v[152:155], v132
	ds_read_b128 v[156:159], v132 offset:2048
	ds_read_b128 v[160:163], v132 offset:4096
	ds_read_b128 v[164:167], v132 offset:6144
	s_waitcnt lgkmcnt(4)
	v_mfma_f32_16x16x32_bf16 v[52:55], v[90:93], v[94:97], v[52:55]
	v_mfma_f32_16x16x32_bf16 v[48:51], v[90:93], v[102:105], v[48:51]
	v_mfma_f32_16x16x32_bf16 v[44:47], v[90:93], v[110:113], v[44:47]
	v_mfma_f32_16x16x32_bf16 v[40:43], v[90:93], v[118:121], v[40:43]
	ds_read_b128 v[168:171], v133 offset:16384
	ds_read_b128 v[172:175], v133 offset:18432
	ds_read_b128 v[176:179], v133 offset:20480
	ds_read_b128 v[180:183], v133 offset:22528
	v_add_u32_e32 v128, s10, v85
	s_add_i32 s10, s12, 32
	v_add_u32_e32 v134, s10, v88
	v_add_u32_e32 v135, s10, v89
	v_readfirstlane_b32 s12, v128
	s_waitcnt lgkmcnt(0)
	s_barrier
	v_lshl_add_u64 v[130:131], v[64:65], 0, s[0:1]
	s_mov_b32 m0, s12
	s_nop 0
	global_load_lds_dwordx4 v[130:131], off
	v_mfma_f32_16x16x32_bf16 v[36:39], v[98:101], v[94:97], v[36:39]
	v_lshl_add_u64 v[130:131], v[72:73], 0, s[0:1]
	s_add_i32 m0, s12, 0x4000
	s_nop 0
	global_load_lds_dwordx4 v[130:131], off
	v_mfma_f32_16x16x32_bf16 v[32:35], v[98:101], v[102:105], v[32:35]
	v_mfma_f32_16x16x32_bf16 v[28:31], v[98:101], v[110:113], v[28:31]
	v_lshl_add_u64 v[130:131], v[66:67], 0, s[0:1]
	s_add_i32 m0, s12, 0x400
	s_nop 0
	global_load_lds_dwordx4 v[130:131], off
	v_mfma_f32_16x16x32_bf16 v[24:27], v[98:101], v[118:121], v[24:27]
	v_lshl_add_u64 v[130:131], v[74:75], 0, s[0:1]
	s_add_i32 m0, s12, 0x4400
	s_nop 0
	global_load_lds_dwordx4 v[130:131], off
	v_mfma_f32_16x16x32_bf16 v[20:23], v[106:109], v[94:97], v[20:23]
	v_mfma_f32_16x16x32_bf16 v[16:19], v[106:109], v[102:105], v[16:19]
	v_lshl_add_u64 v[130:131], v[68:69], 0, s[0:1]
	s_add_i32 m0, s12, 0x800
	s_nop 0
	global_load_lds_dwordx4 v[130:131], off
	v_mfma_f32_16x16x32_bf16 v[12:15], v[106:109], v[110:113], v[12:15]
	v_lshl_add_u64 v[130:131], v[76:77], 0, s[0:1]
	s_add_i32 m0, s12, 0x4800
	s_nop 0
	global_load_lds_dwordx4 v[130:131], off
	v_mfma_f32_16x16x32_bf16 v[8:11], v[106:109], v[118:121], v[8:11]
	v_mfma_f32_16x16x32_bf16 v[4:7], v[114:117], v[94:97], v[4:7]
	v_lshl_add_u64 v[130:131], v[70:71], 0, s[0:1]
	s_add_i32 m0, s12, 0xc00
	s_nop 0
	global_load_lds_dwordx4 v[130:131], off
	v_mfma_f32_16x16x32_bf16 v[0:3], v[114:117], v[102:105], v[0:3]
	v_lshl_add_u64 v[130:131], v[78:79], 0, s[0:1]
	s_add_i32 m0, s12, 0x4c00
	s_nop 0
	global_load_lds_dwordx4 v[130:131], off
	v_mfma_f32_16x16x32_bf16 v[60:63], v[114:117], v[110:113], v[60:63]
	v_mfma_f32_16x16x32_bf16 v[56:59], v[114:117], v[118:121], v[56:59]
	s_waitcnt vmcnt(8)
	s_barrier
	v_add_u32_e32 v132, v134, v87
	v_add_u32_e32 v133, v135, v87
	ds_read_b128 v[90:93], v132
	ds_read_b128 v[98:101], v132 offset:2048
	ds_read_b128 v[106:109], v132 offset:4096
	ds_read_b128 v[114:117], v132 offset:6144
	ds_read_b128 v[94:97], v133 offset:16384
	ds_read_b128 v[102:105], v133 offset:18432
	ds_read_b128 v[110:113], v133 offset:20480
	ds_read_b128 v[118:121], v133 offset:22528
	v_mfma_f32_16x16x32_bf16 v[52:55], v[152:155], v[168:171], v[52:55]
	v_mfma_f32_16x16x32_bf16 v[48:51], v[152:155], v[172:175], v[48:51]
	v_mfma_f32_16x16x32_bf16 v[44:47], v[152:155], v[176:179], v[44:47]
	v_mfma_f32_16x16x32_bf16 v[40:43], v[152:155], v[180:183], v[40:43]
	v_mfma_f32_16x16x32_bf16 v[36:39], v[156:159], v[168:171], v[36:39]
	v_mfma_f32_16x16x32_bf16 v[32:35], v[156:159], v[172:175], v[32:35]
	v_mfma_f32_16x16x32_bf16 v[28:31], v[156:159], v[176:179], v[28:31]
	v_mfma_f32_16x16x32_bf16 v[24:27], v[156:159], v[180:183], v[24:27]
	v_mfma_f32_16x16x32_bf16 v[20:23], v[160:163], v[168:171], v[20:23]
	v_mfma_f32_16x16x32_bf16 v[16:19], v[160:163], v[172:175], v[16:19]
	v_mfma_f32_16x16x32_bf16 v[12:15], v[160:163], v[176:179], v[12:15]
	v_mfma_f32_16x16x32_bf16 v[8:11], v[160:163], v[180:183], v[8:11]
	v_mfma_f32_16x16x32_bf16 v[4:7], v[164:167], v[168:171], v[4:7]
	v_mfma_f32_16x16x32_bf16 v[0:3], v[164:167], v[172:175], v[0:3]
	v_mfma_f32_16x16x32_bf16 v[60:63], v[164:167], v[176:179], v[60:63]
	v_mfma_f32_16x16x32_bf16 v[56:59], v[164:167], v[180:183], v[56:59]
	s_add_i32 s8, s8, 0x8000
	s_add_u32 s0, s0, 0x80
	s_addc_u32 s1, s1, 0
	s_cmpk_lg_i32 s0, 0x780
	s_cbranch_scc1 .Lg255_loop
	s_and_b32 s10, s8, 0x8000
	s_xor_b32 s12, s10, 0x8000
	v_add_u32_e32 v132, v134, v86
	v_add_u32_e32 v133, v135, v86
	ds_read_b128 v[152:155], v132
	ds_read_b128 v[156:159], v132 offset:2048
	ds_read_b128 v[160:163], v132 offset:4096
	ds_read_b128 v[164:167], v132 offset:6144
	s_waitcnt lgkmcnt(4)
	v_mfma_f32_16x16x32_bf16 v[52:55], v[90:93], v[94:97], v[52:55]
	v_mfma_f32_16x16x32_bf16 v[48:51], v[90:93], v[102:105], v[48:51]
	v_mfma_f32_16x16x32_bf16 v[44:47], v[90:93], v[110:113], v[44:47]
	v_mfma_f32_16x16x32_bf16 v[40:43], v[90:93], v[118:121], v[40:43]
	ds_read_b128 v[168:171], v133 offset:16384
	ds_read_b128 v[172:175], v133 offset:18432
	ds_read_b128 v[176:179], v133 offset:20480
	ds_read_b128 v[180:183], v133 offset:22528
	v_mfma_f32_16x16x32_bf16 v[36:39], v[98:101], v[94:97], v[36:39]
	v_mfma_f32_16x16x32_bf16 v[32:35], v[98:101], v[102:105], v[32:35]
	v_mfma_f32_16x16x32_bf16 v[28:31], v[98:101], v[110:113], v[28:31]
	v_mfma_f32_16x16x32_bf16 v[24:27], v[98:101], v[118:121], v[24:27]
	v_mfma_f32_16x16x32_bf16 v[20:23], v[106:109], v[94:97], v[20:23]
	v_mfma_f32_16x16x32_bf16 v[16:19], v[106:109], v[102:105], v[16:19]
	v_mfma_f32_16x16x32_bf16 v[12:15], v[106:109], v[110:113], v[12:15]
	v_mfma_f32_16x16x32_bf16 v[8:11], v[106:109], v[118:121], v[8:11]
	v_mfma_f32_16x16x32_bf16 v[4:7], v[114:117], v[94:97], v[4:7]
	v_mfma_f32_16x16x32_bf16 v[0:3], v[114:117], v[102:105], v[0:3]
	v_mfma_f32_16x16x32_bf16 v[60:63], v[114:117], v[110:113], v[60:63]
	v_mfma_f32_16x16x32_bf16 v[56:59], v[114:117], v[118:121], v[56:59]
	s_waitcnt vmcnt(0) lgkmcnt(0)
	s_barrier
	v_mfma_f32_16x16x32_bf16 v[52:55], v[152:155], v[168:171], v[52:55]
	v_mfma_f32_16x16x32_bf16 v[48:51], v[152:155], v[172:175], v[48:51]
	v_mfma_f32_16x16x32_bf16 v[44:47], v[152:155], v[176:179], v[44:47]
	v_mfma_f32_16x16x32_bf16 v[40:43], v[152:155], v[180:183], v[40:43]
	v_mfma_f32_16x16x32_bf16 v[36:39], v[156:159], v[168:171], v[36:39]
	v_mfma_f32_16x16x32_bf16 v[32:35], v[156:159], v[172:175], v[32:35]
	v_mfma_f32_16x16x32_bf16 v[28:31], v[156:159], v[176:179], v[28:31]
	v_mfma_f32_16x16x32_bf16 v[24:27], v[156:159], v[180:183], v[24:27]
	v_mfma_f32_16x16x32_bf16 v[20:23], v[160:163], v[168:171], v[20:23]
	v_mfma_f32_16x16x32_bf16 v[16:19], v[160:163], v[172:175], v[16:19]
	v_mfma_f32_16x16x32_bf16 v[12:15], v[160:163], v[176:179], v[12:15]
	v_mfma_f32_16x16x32_bf16 v[8:11], v[160:163], v[180:183], v[8:11]
	v_mfma_f32_16x16x32_bf16 v[4:7], v[164:167], v[168:171], v[4:7]
	v_mfma_f32_16x16x32_bf16 v[0:3], v[164:167], v[172:175], v[0:3]
	v_mfma_f32_16x16x32_bf16 v[60:63], v[164:167], v[176:179], v[60:63]
	v_mfma_f32_16x16x32_bf16 v[56:59], v[164:167], v[180:183], v[56:59]
	v_add_u32_e32 v112, 32, v88
	v_add_u32_e32 v100, v112, v87
	ds_read_b128 v[92:95], v100 offset:36864
	ds_read_b128 v[64:67], v100 offset:32768
	ds_read_b128 v[72:75], v100 offset:38912
	ds_read_b128 v[100:103], v100 offset:34816
	v_add_u32_e32 v85, 32, v89
	v_add_u32_e32 v87, v85, v87
	ds_read_b128 v[88:91], v87 offset:53248
	ds_read_b128 v[68:71], v87 offset:55296
	ds_read_b128 v[76:79], v87 offset:49152
	ds_read_b128 v[96:99], v87 offset:51200
	s_waitcnt lgkmcnt(3)
	v_mfma_f32_16x16x32_bf16 v[108:111], v[92:95], v[88:91], v[12:15]
	v_and_or_b32 v81, v81, 64, s3
	s_movk_i32 s0, 0x3fff
	s_nop 0
	v_add_u32_e32 v12, v112, v86
	s_waitcnt lgkmcnt(1)
	v_mfma_f32_16x16x32_bf16 v[52:55], v[64:67], v[76:79], v[52:55]
	v_add_u32_e32 v13, v85, v86
	s_waitcnt lgkmcnt(0)
	v_mfma_f32_16x16x32_bf16 v[48:51], v[64:67], v[96:99], v[48:51]
	v_mfma_f32_16x16x32_bf16 v[104:107], v[64:67], v[88:91], v[44:47]
	v_mfma_f32_16x16x32_bf16 v[40:43], v[64:67], v[68:71], v[40:43]
	v_mfma_f32_16x16x32_bf16 v[36:39], v[100:103], v[76:79], v[36:39]
	v_mfma_f32_16x16x32_bf16 v[32:35], v[100:103], v[96:99], v[32:35]
	v_mfma_f32_16x16x32_bf16 v[64:67], v[100:103], v[88:91], v[28:31]
	v_mfma_f32_16x16x32_bf16 v[24:27], v[100:103], v[68:71], v[24:27]
	v_mfma_f32_16x16x32_bf16 v[100:103], v[92:95], v[76:79], v[20:23]
	v_mfma_f32_16x16x32_bf16 v[16:19], v[92:95], v[96:99], v[16:19]
	v_mfma_f32_16x16x32_bf16 v[8:11], v[92:95], v[68:71], v[8:11]
	v_mfma_f32_16x16x32_bf16 v[76:79], v[72:75], v[76:79], v[4:7]
	v_mfma_f32_16x16x32_bf16 v[0:3], v[72:75], v[96:99], v[0:3]
	v_mfma_f32_16x16x32_bf16 v[88:91], v[72:75], v[88:91], v[60:63]
	v_mfma_f32_16x16x32_bf16 v[68:71], v[72:75], v[68:71], v[56:59]
	ds_read_b128 v[4:7], v12 offset:32768
	ds_read_b128 v[96:99], v12 offset:36864
	ds_read_b128 v[116:119], v12 offset:38912
	ds_read_b128 v[56:59], v12 offset:34816
	ds_read_b128 v[72:75], v13 offset:49152
	ds_read_b128 v[92:95], v13 offset:51200
	ds_read_b128 v[112:115], v13 offset:53248
	ds_read_b128 v[120:123], v13 offset:55296
	s_waitcnt lgkmcnt(3)
	v_mfma_f32_16x16x32_bf16 v[60:63], v[4:7], v[72:75], v[52:55]
	s_waitcnt vmcnt(0)
	s_waitcnt lgkmcnt(0)
	s_barrier
	v_mfma_f32_16x16x32_bf16 v[44:47], v[4:7], v[92:95], v[48:51]
	v_mfma_f32_16x16x32_bf16 v[28:31], v[4:7], v[112:115], v[104:107]
	v_mfma_f32_16x16x32_bf16 v[12:15], v[4:7], v[120:123], v[40:43]
	v_mfma_f32_16x16x32_bf16 v[52:55], v[56:59], v[72:75], v[36:39]
	v_mfma_f32_16x16x32_bf16 v[36:39], v[56:59], v[92:95], v[32:35]
	v_mfma_f32_16x16x32_bf16 v[20:23], v[56:59], v[112:115], v[64:67]
	v_mfma_f32_16x16x32_bf16 v[4:7], v[56:59], v[120:123], v[24:27]
	s_nop 1
	v_or_b32_e32 v66, v81, v84
	v_cmp_lt_i32_e32 vcc, s0, v66
	v_mfma_f32_16x16x32_bf16 v[56:59], v[96:99], v[72:75], v[100:103]
	v_mfma_f32_16x16x32_bf16 v[40:43], v[96:99], v[92:95], v[16:19]
	v_mfma_f32_16x16x32_bf16 v[24:27], v[96:99], v[112:115], v[108:111]
	v_mfma_f32_16x16x32_bf16 v[8:11], v[96:99], v[120:123], v[8:11]
	v_mfma_f32_16x16x32_bf16 v[48:51], v[116:119], v[72:75], v[76:79]
	v_mfma_f32_16x16x32_bf16 v[32:35], v[116:119], v[92:95], v[0:3]
	v_mfma_f32_16x16x32_bf16 v[16:19], v[116:119], v[112:115], v[88:91]
	v_mfma_f32_16x16x32_bf16 v[0:3], v[116:119], v[120:123], v[68:71]
	s_and_saveexec_b64 s[0:1], vcc
	s_xor_b64 s[0:1], exec, s[0:1]
	s_addk_i32 s3, 0xc000
	s_lshr_b32 s3, s3, 8
	v_and_b32_e32 v64, 0xcf, v66
	v_or_b32_e32 v192, 0x2000, v64
	v_mov_b32_e32 v65, s3
	s_andn2_saveexec_b64 s[0:1], s[0:1]
	s_ashr_i32 s3, s13, 13
	v_and_b32_e32 v192, 0x1fcf, v66
	v_mov_b32_e32 v65, s3
	s_or_b64 exec, exec, s[0:1]
	v_add_u32_e32 v64, s2, v83
	s_movk_i32 s0, 0x17f
	v_cmp_lt_i32_e64 s[48:49], s0, v64
	s_movk_i32 s0, 0x480
	s_movk_i32 s2, 0x780
	v_subrev_co_u32_e32 v67, vcc, 0x380, v64
	v_cmp_gt_u32_e64 s[42:43], s0, v64
	s_movk_i32 s0, 0x47f
	v_cmp_eq_u32_e64 s[2:3], s2, v64
	s_xor_b64 s[88:89], vcc, -1
	v_cmp_lt_u32_e32 vcc, s0, v64
	v_and_b32_e32 v68, 0x7fffff80, v64
	s_movk_i32 s0, 0x700
	v_writelane_b32 v255, s2, 20
	v_cmp_ne_u32_e64 s[0:1], s0, v68
	s_and_b64 s[14:15], vcc, s[0:1]
	v_writelane_b32 v255, s3, 21
	s_movk_i32 s2, 0x680
	v_subrev_co_u32_e32 v68, vcc, 0x700, v64
	v_cmp_gt_u32_e64 s[44:45], s2, v64
	s_movk_i32 s2, 0x280
	v_mov_b32_e32 v69, 0xfffff980
	v_mov_b32_e32 v70, 0xfffffb80
	v_ashrrev_i32_e32 v78, 6, v68
	v_lshrrev_b32_e32 v79, 6, v67
	v_mov_b32_e32 v67, 0xfffffd80
	v_mov_b32_e32 v68, 0xfffffe80
	v_cmp_gt_u32_e64 s[40:41], s2, v64
	v_cndmask_b32_e64 v69, v69, v70, s[44:45]
	v_add_u32_e32 v69, v69, v64
	v_cndmask_b32_e64 v67, v67, v68, s[40:41]
	v_add_u32_e32 v67, v67, v64
	s_xor_b64 s[0:1], vcc, -1
	v_lshlrev_b32_e32 v76, 3, v80
	v_lshlrev_b32_e32 v74, 2, v80
	v_lshrrev_b32_e32 v75, 6, v69
	v_ashrrev_i32_e32 v77, 5, v67
	v_cmp_gt_u32_e64 s[38:39], 16, v82
	s_and_saveexec_b64 s[2:3], s[48:49]
	s_xor_b64 s[90:91], exec, s[2:3]
	s_cbranch_execz .LBB0_286
	v_cmp_gt_u32_e64 s[50:51], s33, v192
	s_and_saveexec_b64 s[2:3], s[88:89]
	s_xor_b64 s[92:93], exec, s[2:3]
	s_cbranch_execz .LBB0_279
	s_and_saveexec_b64 s[2:3], s[14:15]
	s_xor_b64 s[94:95], exec, s[2:3]
	s_cbranch_execz .LBB0_276
	s_and_saveexec_b64 s[2:3], s[0:1]
	s_xor_b64 s[46:47], exec, s[2:3]
	s_cbranch_execz .LBB0_269
	s_mov_b64 vcc, exec
	v_readlane_b32 s2, v255, 20
	v_readlane_b32 s3, v255, 21
	s_and_b64 s[2:3], vcc, s[2:3]
	s_mov_b64 exec, s[2:3]
	s_cbranch_execz .LBB0_268
	s_and_saveexec_b64 s[2:3], s[50:51]
	s_cbranch_execz .LBB0_267
	v_readlane_b32 s16, v254, 9
	v_lshlrev_b32_e32 v48, 7, v192
	v_mov_b32_e32 v49, v193
	v_readlane_b32 s24, v254, 17
	v_readlane_b32 s25, v254, 18
	v_lshlrev_b32_e32 v50, 2, v76
	v_mov_b32_e32 v51, v193
	v_lshl_add_u64 v[48:49], s[24:25], 0, v[48:49]
	v_lshl_add_u64 v[56:57], v[48:49], 0, v[50:51]
	global_load_dwordx4 v[48:51], v[56:57], off
	s_nop 0
	global_load_dwordx4 v[56:59], v[56:57], off offset:16
	v_readlane_b32 s30, v254, 23
	v_readlane_b32 s31, v254, 24
	s_movk_i32 s30, 0x4000
	s_mov_b32 s31, s9
	v_readlane_b32 s17, v254, 10
	v_readlane_b32 s18, v254, 11
	v_readlane_b32 s19, v254, 12
	v_readlane_b32 s20, v254, 13
	v_readlane_b32 s21, v254, 14
	v_readlane_b32 s22, v254, 15
	v_readlane_b32 s23, v254, 16
	v_readlane_b32 s26, v254, 19
	v_readlane_b32 s27, v254, 20
	v_readlane_b32 s28, v254, 21
	v_readlane_b32 s29, v254, 22
	s_waitcnt vmcnt(1)
	v_mov_b32_e32 v68, v49
	s_waitcnt vmcnt(0)
	v_mov_b32_e32 v70, v57
	v_mov_b32_e32 v71, v59
	v_mov_b32_e32 v69, v51
	v_mov_b32_e32 v57, v58
	v_mov_b32_e32 v49, v50
	v_pk_mul_f32 v[50:51], v[54:55], v[70:71]
	v_pk_mul_f32 v[58:59], v[52:53], v[68:69]
	v_pk_mul_f32 v[52:53], v[52:53], v[48:49]
	v_pk_mul_f32 v[54:55], v[54:55], v[56:57]
	v_pk_fma_f32 v[50:51], v[62:63], v[56:57], v[50:51] neg_lo:[0,0,1] neg_hi:[0,0,1]
	v_pk_fma_f32 v[48:49], v[60:61], v[48:49], v[58:59] neg_lo:[0,0,1] neg_hi:[0,0,1]
	v_pk_fma_f32 v[54:55], v[62:63], v[70:71], v[54:55]
	v_pk_fma_f32 v[52:53], v[60:61], v[68:69], v[52:53]
	v_mov_b64_e32 v[62:63], v[50:51]
	v_mov_b64_e32 v[60:61], v[48:49]
